# grid-barrier poll latency: s_sleep 1 in the 34 barrier spin loops replaced by s_nop 0
# baseline (speedup 1.0000x reference)
.LBB0_65:
	s_nop 0
	global_load_dword v2, v0, s[6:7] offset:32 sc1
	s_waitcnt vmcnt(0)
	v_and_b32_e32 v2, 0xffff0000, v2
	v_cmp_ne_u32_e32 vcc, v2, v1
	s_or_b64 s[8:9], vcc, s[8:9]
	s_andn2_b64 exec, exec, s[8:9]
	s_cbranch_execnz .LBB0_65

; __device__ __forceinline__ unsigned xb_ld(unsigned* p)              { return __hip_atomic_load(p, __ATOMIC_RELAXED, __HIP_MEMORY_SCOPE_AGENT); }
; #define G lgrid()
; __device__ __forceinline__ void xcd_barrier_complete(unsigned* bar, unsigned x, unsigned& nloc, unsigned& nx) {
;     const unsigned G = gridDim.x * gridDim.y * gridDim.z;
;     unsigned sum, cnt, mine, sp = 0u;
;     for (;;) {
;         sum = 0u; cnt = 0u; mine = 0u;
; #pragma unroll
;         for (unsigned j = 0; j < 16; ++j) { const unsigned c = xb_ld(&bar[XB_XCNT(j)]); sum += c; cnt += (c > 0u) ? 1u : 0u; mine = (j == x) ? c : mine; }
;         if (sum == G) break;
;         __builtin_amdgcn_s_sleep(1);
;         if ((++sp & 255u) == 0u) { if (xb_ld(&bar[XB_TMO])) break; if (sp > XB_SPIN_CAP) { atomicAdd(&bar[XB_TMO], 1u); break; } }
;     }
;     nloc = mine > 0u ? mine : 1u; nx = cnt > 0u ? cnt : 1u;
; }
.LBB0_212:
	global_load_dword v15, v16, s[50:51] offset:1024 sc1
	s_waitcnt lgkmcnt(0)
	global_load_dword v0, v16, s[50:51] offset:1280 sc1
	global_load_dword v1, v16, s[50:51] offset:1536 sc1
	global_load_dword v2, v16, s[50:51] offset:1792 sc1
	global_load_dword v3, v16, s[50:51] offset:2048 sc1
	global_load_dword v4, v16, s[50:51] offset:2304 sc1
	global_load_dword v5, v16, s[50:51] offset:2560 sc1
	global_load_dword v6, v16, s[50:51] offset:2816 sc1
	global_load_dword v7, v16, s[50:51] offset:3072 sc1
	global_load_dword v8, v16, s[50:51] offset:3328 sc1
	global_load_dword v9, v16, s[50:51] offset:3584 sc1
	global_load_dword v10, v16, s[50:51] offset:3840 sc1
	global_load_dword v11, v16, s[6:7] sc1
	global_load_dword v12, v16, s[8:9] sc1
	global_load_dword v13, v16, s[10:11] sc1
	global_load_dword v14, v16, s[12:13] sc1
	s_mov_b64 s[14:15], -1
	s_mov_b64 s[16:17], -1
	s_waitcnt vmcnt(14)
	v_add_u32_e32 v17, v0, v15
	s_waitcnt vmcnt(13)
	v_add_u32_e32 v17, v17, v1
	s_waitcnt vmcnt(12)
	v_add_u32_e32 v17, v17, v2
	s_waitcnt vmcnt(11)
	v_add_u32_e32 v17, v17, v3
	s_waitcnt vmcnt(10)
	v_add_u32_e32 v17, v17, v4
	s_waitcnt vmcnt(9)
	v_add_u32_e32 v17, v17, v5
	s_waitcnt vmcnt(8)
	v_add_u32_e32 v17, v17, v6
	s_waitcnt vmcnt(7)
	v_add_u32_e32 v17, v17, v7
	s_waitcnt vmcnt(6)
	v_add_u32_e32 v17, v17, v8
	s_waitcnt vmcnt(5)
	v_add_u32_e32 v17, v17, v9
	s_waitcnt vmcnt(4)
	v_add_u32_e32 v17, v17, v10
	s_waitcnt vmcnt(3)
	v_add_u32_e32 v17, v17, v11
	s_waitcnt vmcnt(2)
	v_add_u32_e32 v17, v17, v12
	s_waitcnt vmcnt(1)
	v_add_u32_e32 v17, v17, v13
	s_waitcnt vmcnt(0)
	v_add_u32_e32 v17, v17, v14
	v_cmp_eq_u32_e32 vcc, s2, v17
	s_cbranch_vccnz .LBB0_211
	s_and_b32 s14, s20, 0xff
	s_cmp_eq_u32 s14, 0
	s_mov_b64 s[14:15], -1
	s_mov_b64 s[18:19], -1
	s_nop 0
	s_cbranch_scc0 .LBB0_216
	global_load_dword v17, v16, s[50:51] offset:512 sc1
	s_waitcnt vmcnt(0)
	v_cmp_eq_u32_e32 vcc, 0, v17
	s_cbranch_vccnz .LBB0_218
	s_mov_b64 s[18:19], 0

; __device__ __forceinline__ unsigned xb_ld(unsigned* p)              { return __hip_atomic_load(p, __ATOMIC_RELAXED, __HIP_MEMORY_SCOPE_AGENT); }
; __device__ __forceinline__ unsigned xb_add(unsigned* p, unsigned v) { return __hip_atomic_fetch_add(p, v, __ATOMIC_RELAXED, __HIP_MEMORY_SCOPE_AGENT); }
; #define XB_SPIN(cond, bar) do { unsigned _sp = 0; while (cond) { __builtin_amdgcn_s_sleep(1); \
;     if ((++_sp & 255u) == 0u) { if (xb_ld(&(bar)[XB_TMO])) break; if (_sp > XB_SPIN_CAP) { atomicAdd(&(bar)[XB_TMO], 1u); break; } } } } while (0)
; __device__ __forceinline__ void xcd_barrier(const XcdBarrier& b) {
;     ...
;             else XB_SPIN(xb_ld(&bar[XB_TOPGEN]) == tg, bar);
;             __builtin_amdgcn_fence(__ATOMIC_ACQUIRE, "agent");
;             xb_add(&bar[XB_XGEN(b.x)], 1u);
;             asm volatile("s_waitcnt vmcnt(0)" ::: "memory");
;         } else {
;             XB_SPIN(xb_ld(&bar[XB_XGEN(b.x)]) == gen, bar);
.LBB0_227:
	s_and_b32 s20, s2, 0xff
	s_mov_b64 s[18:19], -1
	s_cmp_lg_u32 s20, 0
	s_mov_b64 s[22:23], -1
	s_nop 0
	s_cbranch_scc1 .LBB0_230
	global_load_dword v2, v0, s[50:51] offset:512 sc1
	s_waitcnt vmcnt(0)
	v_cmp_eq_u32_e32 vcc, 0, v2
	s_cbranch_vccnz .LBB0_232
	s_mov_b64 s[22:23], 0
	s_mov_b64 s[20:21], -1

; __device__ __forceinline__ unsigned xb_ld(unsigned* p)              { return __hip_atomic_load(p, __ATOMIC_RELAXED, __HIP_MEMORY_SCOPE_AGENT); }
; __device__ __forceinline__ unsigned xb_add(unsigned* p, unsigned v) { return __hip_atomic_fetch_add(p, v, __ATOMIC_RELAXED, __HIP_MEMORY_SCOPE_AGENT); }
; #define XB_SPIN(cond, bar) do { unsigned _sp = 0; while (cond) { __builtin_amdgcn_s_sleep(1); \
;     if ((++_sp & 255u) == 0u) { if (xb_ld(&(bar)[XB_TMO])) break; if (_sp > XB_SPIN_CAP) { atomicAdd(&(bar)[XB_TMO], 1u); break; } } } } while (0)
; __device__ __forceinline__ void xcd_barrier(const XcdBarrier& b) {
;     ...
;             else XB_SPIN(xb_ld(&bar[XB_TOPGEN]) == tg, bar);
;             __builtin_amdgcn_fence(__ATOMIC_ACQUIRE, "agent");
;             xb_add(&bar[XB_XGEN(b.x)], 1u);
;             asm volatile("s_waitcnt vmcnt(0)" ::: "memory");
;         } else {
;             XB_SPIN(xb_ld(&bar[XB_XGEN(b.x)]) == gen, bar);
.LBB0_241:
	s_and_b32 s20, s2, 0xff
	s_cmp_lg_u32 s20, 0
	s_mov_b64 s[22:23], -1
	s_nop 0
	s_cbranch_scc1 .LBB0_244
	global_load_dword v1, v0, s[12:13] sc1
	s_waitcnt vmcnt(0)
	v_cmp_eq_u32_e32 vcc, 0, v1
	s_cbranch_vccnz .LBB0_246
	s_mov_b64 s[22:23], 0
	s_mov_b64 s[20:21], -1

; __device__ __forceinline__ unsigned xb_ld(unsigned* p)              { return __hip_atomic_load(p, __ATOMIC_RELAXED, __HIP_MEMORY_SCOPE_AGENT); }
; #define G lgrid()
; __device__ __forceinline__ void xcd_barrier_complete(unsigned* bar, unsigned x, unsigned& nloc, unsigned& nx) {
;     const unsigned G = gridDim.x * gridDim.y * gridDim.z;
;     unsigned sum, cnt, mine, sp = 0u;
;     for (;;) {
;         sum = 0u; cnt = 0u; mine = 0u;
; #pragma unroll
;         for (unsigned j = 0; j < 16; ++j) { const unsigned c = xb_ld(&bar[XB_XCNT(j)]); sum += c; cnt += (c > 0u) ? 1u : 0u; mine = (j == x) ? c : mine; }
;         if (sum == G) break;
;         __builtin_amdgcn_s_sleep(1);
;         if ((++sp & 255u) == 0u) { if (xb_ld(&bar[XB_TMO])) break; if (sp > XB_SPIN_CAP) { atomicAdd(&bar[XB_TMO], 1u); break; } }
;     }
;     nloc = mine > 0u ? mine : 1u; nx = cnt > 0u ? cnt : 1u;
; }
.LBB0_536:
	v_readlane_b32 s10, v255, 1
	v_readlane_b32 s11, v255, 2
	global_load_dword v12, v129, s[50:51] offset:1024 sc1
	global_load_dword v0, v129, s[50:51] offset:1280 sc1
	s_waitcnt lgkmcnt(0)
	global_load_dword v1, v129, s[50:51] offset:1536 sc1
	global_load_dword v2, v129, s[50:51] offset:1792 sc1
	global_load_dword v3, v129, s[50:51] offset:2048 sc1
	global_load_dword v4, v129, s[50:51] offset:2304 sc1
	global_load_dword v5, v129, s[50:51] offset:2560 sc1
	global_load_dword v6, v129, s[50:51] offset:2816 sc1
	global_load_dword v7, v129, s[50:51] offset:3072 sc1
	global_load_dword v8, v129, s[50:51] offset:3328 sc1
	global_load_dword v9, v129, s[50:51] offset:3584 sc1
	global_load_dword v10, v129, s[50:51] offset:3840 sc1
	global_load_dword v11, v129, s[38:39] sc1
	global_load_dword v13, v129, s[10:11] sc1
	v_readlane_b32 s10, v255, 5
	v_readlane_b32 s11, v255, 6
	s_mov_b64 s[12:13], -1
	s_waitcnt vmcnt(12)
	v_add_u32_e32 v16, v0, v12
	s_nop 1
	global_load_dword v14, v129, s[10:11] sc1
	v_readlane_b32 s10, v255, 7
	v_readlane_b32 s11, v255, 8
	s_waitcnt vmcnt(12)
	v_add_u32_e32 v16, v16, v1
	s_waitcnt vmcnt(11)
	v_add_u32_e32 v16, v16, v2
	s_waitcnt vmcnt(10)
	v_add_u32_e32 v16, v16, v3
	s_waitcnt vmcnt(9)
	v_add_u32_e32 v16, v16, v4
	s_waitcnt vmcnt(8)
	v_add_u32_e32 v16, v16, v5
	global_load_dword v15, v129, s[10:11] sc1
	s_waitcnt vmcnt(8)
	v_add_u32_e32 v16, v16, v6
	s_waitcnt vmcnt(7)
	v_add_u32_e32 v16, v16, v7
	s_waitcnt vmcnt(6)
	v_add_u32_e32 v16, v16, v8
	s_waitcnt vmcnt(5)
	v_add_u32_e32 v16, v16, v9
	s_waitcnt vmcnt(4)
	v_add_u32_e32 v16, v16, v10
	s_waitcnt vmcnt(3)
	v_add_u32_e32 v16, v16, v11
	s_waitcnt vmcnt(2)
	v_add_u32_e32 v16, v16, v13
	s_mov_b64 s[10:11], -1
	s_waitcnt vmcnt(1)
	v_add_u32_e32 v16, v16, v14
	s_waitcnt vmcnt(0)
	v_add_u32_e32 v16, v16, v15
	v_cmp_eq_u32_e32 vcc, s48, v16
	s_cbranch_vccnz .LBB0_535
	s_and_b32 s10, s5, 0xff
	s_cmp_eq_u32 s10, 0
	s_mov_b64 s[10:11], -1
	s_mov_b64 s[14:15], -1
	s_nop 0
	s_cbranch_scc0 .LBB0_540
	v_readlane_b32 s10, v255, 3
	v_readlane_b32 s11, v255, 4
	s_nop 4
	global_load_dword v16, v129, s[10:11] sc1
	s_waitcnt vmcnt(0)
	v_cmp_eq_u32_e32 vcc, 0, v16
	s_cbranch_vccnz .LBB0_542
	s_mov_b64 s[14:15], 0
	s_mov_b64 s[10:11], -1

; __device__ __forceinline__ unsigned xb_ld(unsigned* p)              { return __hip_atomic_load(p, __ATOMIC_RELAXED, __HIP_MEMORY_SCOPE_AGENT); }
; __device__ __forceinline__ unsigned xb_add(unsigned* p, unsigned v) { return __hip_atomic_fetch_add(p, v, __ATOMIC_RELAXED, __HIP_MEMORY_SCOPE_AGENT); }
; #define XB_SPIN(cond, bar) do { unsigned _sp = 0; while (cond) { __builtin_amdgcn_s_sleep(1); \
;     if ((++_sp & 255u) == 0u) { if (xb_ld(&(bar)[XB_TMO])) break; if (_sp > XB_SPIN_CAP) { atomicAdd(&(bar)[XB_TMO], 1u); break; } } } } while (0)
; __device__ __forceinline__ void xcd_barrier(const XcdBarrier& b) {
;     ...
;             else XB_SPIN(xb_ld(&bar[XB_TOPGEN]) == tg, bar);
;             __builtin_amdgcn_fence(__ATOMIC_ACQUIRE, "agent");
;             xb_add(&bar[XB_XGEN(b.x)], 1u);
;             asm volatile("s_waitcnt vmcnt(0)" ::: "memory");
;         } else {
;             XB_SPIN(xb_ld(&bar[XB_XGEN(b.x)]) == gen, bar);
.LBB0_550:
	s_and_b32 s20, s5, 0xff
	s_mov_b64 s[18:19], -1
	s_cmp_lg_u32 s20, 0
	s_mov_b64 s[22:23], -1
	s_nop 0
	s_cbranch_scc1 .LBB0_553
	v_readlane_b32 s20, v255, 3
	v_readlane_b32 s21, v255, 4
	s_nop 4
	global_load_dword v1, v129, s[20:21] sc1
	s_waitcnt vmcnt(0)
	v_cmp_eq_u32_e32 vcc, 0, v1
	s_cbranch_vccnz .LBB0_555
	s_mov_b64 s[22:23], 0
	s_mov_b64 s[20:21], -1

; __device__ __forceinline__ unsigned xb_ld(unsigned* p)              { return __hip_atomic_load(p, __ATOMIC_RELAXED, __HIP_MEMORY_SCOPE_AGENT); }
; __device__ __forceinline__ unsigned xb_add(unsigned* p, unsigned v) { return __hip_atomic_fetch_add(p, v, __ATOMIC_RELAXED, __HIP_MEMORY_SCOPE_AGENT); }
; #define XB_SPIN(cond, bar) do { unsigned _sp = 0; while (cond) { __builtin_amdgcn_s_sleep(1); \
;     if ((++_sp & 255u) == 0u) { if (xb_ld(&(bar)[XB_TMO])) break; if (_sp > XB_SPIN_CAP) { atomicAdd(&(bar)[XB_TMO], 1u); break; } } } } while (0)
; __device__ __forceinline__ void xcd_barrier(const XcdBarrier& b) {
;     ...
;             else XB_SPIN(xb_ld(&bar[XB_TOPGEN]) == tg, bar);
;             __builtin_amdgcn_fence(__ATOMIC_ACQUIRE, "agent");
;             xb_add(&bar[XB_XGEN(b.x)], 1u);
;             asm volatile("s_waitcnt vmcnt(0)" ::: "memory");
;         } else {
;             XB_SPIN(xb_ld(&bar[XB_XGEN(b.x)]) == gen, bar);
.LBB0_564:
	s_and_b32 s20, s5, 0xff
	s_mov_b64 s[18:19], -1
	s_cmp_lg_u32 s20, 0
	s_mov_b64 s[22:23], -1
	s_nop 0
	s_cbranch_scc1 .LBB0_567
	v_readlane_b32 s20, v255, 3
	v_readlane_b32 s21, v255, 4
	s_nop 4
	global_load_dword v0, v129, s[20:21] sc1
	s_waitcnt vmcnt(0)
	v_cmp_eq_u32_e32 vcc, 0, v0
	s_cbranch_vccnz .LBB0_569
	s_mov_b64 s[22:23], 0
	s_mov_b64 s[20:21], -1

; __device__ __forceinline__ unsigned xb_ld(unsigned* p)              { return __hip_atomic_load(p, __ATOMIC_RELAXED, __HIP_MEMORY_SCOPE_AGENT); }
; #define G lgrid()
; __device__ __forceinline__ void xcd_barrier_complete(unsigned* bar, unsigned x, unsigned& nloc, unsigned& nx) {
;     const unsigned G = gridDim.x * gridDim.y * gridDim.z;
;     unsigned sum, cnt, mine, sp = 0u;
;     for (;;) {
;         sum = 0u; cnt = 0u; mine = 0u;
; #pragma unroll
;         for (unsigned j = 0; j < 16; ++j) { const unsigned c = xb_ld(&bar[XB_XCNT(j)]); sum += c; cnt += (c > 0u) ? 1u : 0u; mine = (j == x) ? c : mine; }
;         if (sum == G) break;
;         __builtin_amdgcn_s_sleep(1);
;         if ((++sp & 255u) == 0u) { if (xb_ld(&bar[XB_TMO])) break; if (sp > XB_SPIN_CAP) { atomicAdd(&bar[XB_TMO], 1u); break; } }
;     }
;     nloc = mine > 0u ? mine : 1u; nx = cnt > 0u ? cnt : 1u;
; }
.LBB0_896:
	v_readlane_b32 s14, v255, 1
	v_readlane_b32 s15, v255, 2
	global_load_dword v12, v129, s[50:51] offset:1024 sc1
	global_load_dword v0, v129, s[50:51] offset:1280 sc1
	s_waitcnt lgkmcnt(0)
	global_load_dword v1, v129, s[50:51] offset:1536 sc1
	global_load_dword v2, v129, s[50:51] offset:1792 sc1
	global_load_dword v3, v129, s[50:51] offset:2048 sc1
	global_load_dword v4, v129, s[50:51] offset:2304 sc1
	global_load_dword v5, v129, s[50:51] offset:2560 sc1
	global_load_dword v6, v129, s[50:51] offset:2816 sc1
	global_load_dword v7, v129, s[50:51] offset:3072 sc1
	global_load_dword v8, v129, s[50:51] offset:3328 sc1
	global_load_dword v9, v129, s[50:51] offset:3584 sc1
	global_load_dword v10, v129, s[50:51] offset:3840 sc1
	global_load_dword v11, v129, s[38:39] sc1
	global_load_dword v13, v129, s[14:15] sc1
	v_readlane_b32 s14, v255, 5
	v_readlane_b32 s15, v255, 6
	s_mov_b64 s[16:17], -1
	s_waitcnt vmcnt(12)
	v_add_u32_e32 v16, v0, v12
	s_nop 1
	global_load_dword v14, v129, s[14:15] sc1
	v_readlane_b32 s14, v255, 7
	v_readlane_b32 s15, v255, 8
	s_waitcnt vmcnt(12)
	v_add_u32_e32 v16, v16, v1
	s_waitcnt vmcnt(11)
	v_add_u32_e32 v16, v16, v2
	s_waitcnt vmcnt(10)
	v_add_u32_e32 v16, v16, v3
	s_waitcnt vmcnt(9)
	v_add_u32_e32 v16, v16, v4
	s_waitcnt vmcnt(8)
	v_add_u32_e32 v16, v16, v5
	global_load_dword v15, v129, s[14:15] sc1
	s_waitcnt vmcnt(8)
	v_add_u32_e32 v16, v16, v6
	s_waitcnt vmcnt(7)
	v_add_u32_e32 v16, v16, v7
	s_waitcnt vmcnt(6)
	v_add_u32_e32 v16, v16, v8
	s_waitcnt vmcnt(5)
	v_add_u32_e32 v16, v16, v9
	s_waitcnt vmcnt(4)
	v_add_u32_e32 v16, v16, v10
	s_waitcnt vmcnt(3)
	v_add_u32_e32 v16, v16, v11
	s_waitcnt vmcnt(2)
	v_add_u32_e32 v16, v16, v13
	s_mov_b64 s[14:15], -1
	s_waitcnt vmcnt(1)
	v_add_u32_e32 v16, v16, v14
	s_waitcnt vmcnt(0)
	v_add_u32_e32 v16, v16, v15
	v_cmp_eq_u32_e32 vcc, s48, v16
	s_cbranch_vccnz .LBB0_895
	s_and_b32 s14, s5, 0xff
	s_cmp_eq_u32 s14, 0
	s_mov_b64 s[14:15], -1
	s_mov_b64 s[18:19], -1
	s_nop 0
	s_cbranch_scc0 .LBB0_900
	v_readlane_b32 s14, v255, 3
	v_readlane_b32 s15, v255, 4
	s_nop 4
	global_load_dword v16, v129, s[14:15] sc1
	s_waitcnt vmcnt(0)
	v_cmp_eq_u32_e32 vcc, 0, v16
	s_cbranch_vccnz .LBB0_902
	s_mov_b64 s[18:19], 0
	s_mov_b64 s[14:15], -1

; __device__ __forceinline__ unsigned xb_ld(unsigned* p)              { return __hip_atomic_load(p, __ATOMIC_RELAXED, __HIP_MEMORY_SCOPE_AGENT); }
; __device__ __forceinline__ unsigned xb_add(unsigned* p, unsigned v) { return __hip_atomic_fetch_add(p, v, __ATOMIC_RELAXED, __HIP_MEMORY_SCOPE_AGENT); }
; #define XB_SPIN(cond, bar) do { unsigned _sp = 0; while (cond) { __builtin_amdgcn_s_sleep(1); \
;     if ((++_sp & 255u) == 0u) { if (xb_ld(&(bar)[XB_TMO])) break; if (_sp > XB_SPIN_CAP) { atomicAdd(&(bar)[XB_TMO], 1u); break; } } } } while (0)
; __device__ __forceinline__ void xcd_barrier(const XcdBarrier& b) {
;     ...
;             else XB_SPIN(xb_ld(&bar[XB_TOPGEN]) == tg, bar);
;             __builtin_amdgcn_fence(__ATOMIC_ACQUIRE, "agent");
;             xb_add(&bar[XB_XGEN(b.x)], 1u);
;             asm volatile("s_waitcnt vmcnt(0)" ::: "memory");
;         } else {
;             XB_SPIN(xb_ld(&bar[XB_XGEN(b.x)]) == gen, bar);
.LBB0_910:
	s_and_b32 s24, s5, 0xff
	s_mov_b64 s[22:23], -1
	s_cmp_lg_u32 s24, 0
	s_mov_b64 s[26:27], -1
	s_nop 0
	s_cbranch_scc1 .LBB0_913
	v_readlane_b32 s24, v255, 3
	v_readlane_b32 s25, v255, 4
	s_nop 4
	global_load_dword v1, v129, s[24:25] sc1
	s_waitcnt vmcnt(0)
	v_cmp_eq_u32_e32 vcc, 0, v1
	s_cbranch_vccnz .LBB0_915
	s_mov_b64 s[26:27], 0
	s_mov_b64 s[24:25], -1

; __device__ __forceinline__ unsigned xb_ld(unsigned* p)              { return __hip_atomic_load(p, __ATOMIC_RELAXED, __HIP_MEMORY_SCOPE_AGENT); }
; __device__ __forceinline__ unsigned xb_add(unsigned* p, unsigned v) { return __hip_atomic_fetch_add(p, v, __ATOMIC_RELAXED, __HIP_MEMORY_SCOPE_AGENT); }
; #define XB_SPIN(cond, bar) do { unsigned _sp = 0; while (cond) { __builtin_amdgcn_s_sleep(1); \
;     if ((++_sp & 255u) == 0u) { if (xb_ld(&(bar)[XB_TMO])) break; if (_sp > XB_SPIN_CAP) { atomicAdd(&(bar)[XB_TMO], 1u); break; } } } } while (0)
; __device__ __forceinline__ void xcd_barrier(const XcdBarrier& b) {
;     ...
;             else XB_SPIN(xb_ld(&bar[XB_TOPGEN]) == tg, bar);
;             __builtin_amdgcn_fence(__ATOMIC_ACQUIRE, "agent");
;             xb_add(&bar[XB_XGEN(b.x)], 1u);
;             asm volatile("s_waitcnt vmcnt(0)" ::: "memory");
;         } else {
;             XB_SPIN(xb_ld(&bar[XB_XGEN(b.x)]) == gen, bar);
.LBB0_924:
	s_and_b32 s24, s5, 0xff
	s_mov_b64 s[22:23], -1
	s_cmp_lg_u32 s24, 0
	s_mov_b64 s[26:27], -1
	s_nop 0
	s_cbranch_scc1 .LBB0_927
	v_readlane_b32 s24, v255, 3
	v_readlane_b32 s25, v255, 4
	s_nop 4
	global_load_dword v0, v129, s[24:25] sc1
	s_waitcnt vmcnt(0)
	v_cmp_eq_u32_e32 vcc, 0, v0
	s_cbranch_vccnz .LBB0_929
	s_mov_b64 s[26:27], 0
	s_mov_b64 s[24:25], -1

; __device__ __forceinline__ unsigned xb_ld(unsigned* p)              { return __hip_atomic_load(p, __ATOMIC_RELAXED, __HIP_MEMORY_SCOPE_AGENT); }
; #define G lgrid()
; __device__ __forceinline__ void xcd_barrier_complete(unsigned* bar, unsigned x, unsigned& nloc, unsigned& nx) {
;     const unsigned G = gridDim.x * gridDim.y * gridDim.z;
;     unsigned sum, cnt, mine, sp = 0u;
;     for (;;) {
;         sum = 0u; cnt = 0u; mine = 0u;
; #pragma unroll
;         for (unsigned j = 0; j < 16; ++j) { const unsigned c = xb_ld(&bar[XB_XCNT(j)]); sum += c; cnt += (c > 0u) ? 1u : 0u; mine = (j == x) ? c : mine; }
;         if (sum == G) break;
;         __builtin_amdgcn_s_sleep(1);
;         if ((++sp & 255u) == 0u) { if (xb_ld(&bar[XB_TMO])) break; if (sp > XB_SPIN_CAP) { atomicAdd(&bar[XB_TMO], 1u); break; } }
;     }
;     nloc = mine > 0u ? mine : 1u; nx = cnt > 0u ? cnt : 1u;
; }
.LBB0_1137:
	v_readlane_b32 s12, v255, 1
	v_readlane_b32 s13, v255, 2
	global_load_dword v12, v129, s[50:51] offset:1024 sc1
	global_load_dword v0, v129, s[50:51] offset:1280 sc1
	s_waitcnt lgkmcnt(0)
	global_load_dword v1, v129, s[50:51] offset:1536 sc1
	global_load_dword v2, v129, s[50:51] offset:1792 sc1
	global_load_dword v3, v129, s[50:51] offset:2048 sc1
	global_load_dword v4, v129, s[50:51] offset:2304 sc1
	global_load_dword v5, v129, s[50:51] offset:2560 sc1
	global_load_dword v6, v129, s[50:51] offset:2816 sc1
	global_load_dword v7, v129, s[50:51] offset:3072 sc1
	global_load_dword v8, v129, s[50:51] offset:3328 sc1
	global_load_dword v9, v129, s[50:51] offset:3584 sc1
	global_load_dword v10, v129, s[50:51] offset:3840 sc1
	global_load_dword v11, v129, s[38:39] sc1
	global_load_dword v13, v129, s[12:13] sc1
	v_readlane_b32 s12, v255, 5
	v_readlane_b32 s13, v255, 6
	s_mov_b64 s[14:15], -1
	s_waitcnt vmcnt(12)
	v_add_u32_e32 v16, v0, v12
	s_nop 1
	global_load_dword v14, v129, s[12:13] sc1
	v_readlane_b32 s12, v255, 7
	v_readlane_b32 s13, v255, 8
	s_waitcnt vmcnt(12)
	v_add_u32_e32 v16, v16, v1
	s_waitcnt vmcnt(11)
	v_add_u32_e32 v16, v16, v2
	s_waitcnt vmcnt(10)
	v_add_u32_e32 v16, v16, v3
	s_waitcnt vmcnt(9)
	v_add_u32_e32 v16, v16, v4
	s_waitcnt vmcnt(8)
	v_add_u32_e32 v16, v16, v5
	global_load_dword v15, v129, s[12:13] sc1
	s_waitcnt vmcnt(8)
	v_add_u32_e32 v16, v16, v6
	s_waitcnt vmcnt(7)
	v_add_u32_e32 v16, v16, v7
	s_waitcnt vmcnt(6)
	v_add_u32_e32 v16, v16, v8
	s_waitcnt vmcnt(5)
	v_add_u32_e32 v16, v16, v9
	s_waitcnt vmcnt(4)
	v_add_u32_e32 v16, v16, v10
	s_waitcnt vmcnt(3)
	v_add_u32_e32 v16, v16, v11
	s_waitcnt vmcnt(2)
	v_add_u32_e32 v16, v16, v13
	s_mov_b64 s[12:13], -1
	s_waitcnt vmcnt(1)
	v_add_u32_e32 v16, v16, v14
	s_waitcnt vmcnt(0)
	v_add_u32_e32 v16, v16, v15
	v_cmp_eq_u32_e32 vcc, s48, v16
	s_cbranch_vccnz .LBB0_1136
	s_and_b32 s12, s5, 0xff
	s_cmp_eq_u32 s12, 0
	s_mov_b64 s[12:13], -1
	s_mov_b64 s[16:17], -1
	s_nop 0
	s_cbranch_scc0 .LBB0_1141
	v_readlane_b32 s12, v255, 3
	v_readlane_b32 s13, v255, 4
	s_nop 4
	global_load_dword v16, v129, s[12:13] sc1
	s_waitcnt vmcnt(0)
	v_cmp_eq_u32_e32 vcc, 0, v16
	s_cbranch_vccnz .LBB0_1143
	s_mov_b64 s[16:17], 0
	s_mov_b64 s[12:13], -1

; __device__ __forceinline__ unsigned xb_ld(unsigned* p)              { return __hip_atomic_load(p, __ATOMIC_RELAXED, __HIP_MEMORY_SCOPE_AGENT); }
; __device__ __forceinline__ unsigned xb_add(unsigned* p, unsigned v) { return __hip_atomic_fetch_add(p, v, __ATOMIC_RELAXED, __HIP_MEMORY_SCOPE_AGENT); }
; #define XB_SPIN(cond, bar) do { unsigned _sp = 0; while (cond) { __builtin_amdgcn_s_sleep(1); \
;     if ((++_sp & 255u) == 0u) { if (xb_ld(&(bar)[XB_TMO])) break; if (_sp > XB_SPIN_CAP) { atomicAdd(&(bar)[XB_TMO], 1u); break; } } } } while (0)
; __device__ __forceinline__ void xcd_barrier(const XcdBarrier& b) {
;     ...
;             else XB_SPIN(xb_ld(&bar[XB_TOPGEN]) == tg, bar);
;             __builtin_amdgcn_fence(__ATOMIC_ACQUIRE, "agent");
;             xb_add(&bar[XB_XGEN(b.x)], 1u);
;             asm volatile("s_waitcnt vmcnt(0)" ::: "memory");
;         } else {
;             XB_SPIN(xb_ld(&bar[XB_XGEN(b.x)]) == gen, bar);
.LBB0_1151:
	s_and_b32 s22, s5, 0xff
	s_mov_b64 s[20:21], -1
	s_cmp_lg_u32 s22, 0
	s_mov_b64 s[24:25], -1
	s_nop 0
	s_cbranch_scc1 .LBB0_1154
	v_readlane_b32 s22, v255, 3
	v_readlane_b32 s23, v255, 4
	s_nop 4
	global_load_dword v1, v129, s[22:23] sc1
	s_waitcnt vmcnt(0)
	v_cmp_eq_u32_e32 vcc, 0, v1
	s_cbranch_vccnz .LBB0_1156
	s_mov_b64 s[24:25], 0
	s_mov_b64 s[22:23], -1

; __device__ __forceinline__ unsigned xb_ld(unsigned* p)              { return __hip_atomic_load(p, __ATOMIC_RELAXED, __HIP_MEMORY_SCOPE_AGENT); }
; __device__ __forceinline__ unsigned xb_add(unsigned* p, unsigned v) { return __hip_atomic_fetch_add(p, v, __ATOMIC_RELAXED, __HIP_MEMORY_SCOPE_AGENT); }
; #define XB_SPIN(cond, bar) do { unsigned _sp = 0; while (cond) { __builtin_amdgcn_s_sleep(1); \
;     if ((++_sp & 255u) == 0u) { if (xb_ld(&(bar)[XB_TMO])) break; if (_sp > XB_SPIN_CAP) { atomicAdd(&(bar)[XB_TMO], 1u); break; } } } } while (0)
; __device__ __forceinline__ void xcd_barrier(const XcdBarrier& b) {
;     ...
;             else XB_SPIN(xb_ld(&bar[XB_TOPGEN]) == tg, bar);
;             __builtin_amdgcn_fence(__ATOMIC_ACQUIRE, "agent");
;             xb_add(&bar[XB_XGEN(b.x)], 1u);
;             asm volatile("s_waitcnt vmcnt(0)" ::: "memory");
;         } else {
;             XB_SPIN(xb_ld(&bar[XB_XGEN(b.x)]) == gen, bar);
.LBB0_1165:
	s_and_b32 s22, s5, 0xff
	s_mov_b64 s[20:21], -1
	s_cmp_lg_u32 s22, 0
	s_mov_b64 s[24:25], -1
	s_nop 0
	s_cbranch_scc1 .LBB0_1168
	v_readlane_b32 s22, v255, 3
	v_readlane_b32 s23, v255, 4
	s_nop 4
	global_load_dword v0, v129, s[22:23] sc1
	s_waitcnt vmcnt(0)
	v_cmp_eq_u32_e32 vcc, 0, v0
	s_cbranch_vccnz .LBB0_1170
	s_mov_b64 s[24:25], 0
	s_mov_b64 s[22:23], -1

; __device__ __forceinline__ unsigned xb_ld(unsigned* p)              { return __hip_atomic_load(p, __ATOMIC_RELAXED, __HIP_MEMORY_SCOPE_AGENT); }
; #define G lgrid()
; __device__ __forceinline__ void xcd_barrier_complete(unsigned* bar, unsigned x, unsigned& nloc, unsigned& nx) {
;     const unsigned G = gridDim.x * gridDim.y * gridDim.z;
;     unsigned sum, cnt, mine, sp = 0u;
;     for (;;) {
;         sum = 0u; cnt = 0u; mine = 0u;
; #pragma unroll
;         for (unsigned j = 0; j < 16; ++j) { const unsigned c = xb_ld(&bar[XB_XCNT(j)]); sum += c; cnt += (c > 0u) ? 1u : 0u; mine = (j == x) ? c : mine; }
;         if (sum == G) break;
;         __builtin_amdgcn_s_sleep(1);
;         if ((++sp & 255u) == 0u) { if (xb_ld(&bar[XB_TMO])) break; if (sp > XB_SPIN_CAP) { atomicAdd(&bar[XB_TMO], 1u); break; } }
;     }
;     nloc = mine > 0u ? mine : 1u; nx = cnt > 0u ? cnt : 1u;
; }
.LBB0_1219:
	v_readlane_b32 s6, v255, 1
	v_readlane_b32 s7, v255, 2
	global_load_dword v12, v129, s[50:51] offset:1024 sc1
	global_load_dword v0, v129, s[50:51] offset:1280 sc1
	s_waitcnt lgkmcnt(0)
	global_load_dword v1, v129, s[50:51] offset:1536 sc1
	global_load_dword v2, v129, s[50:51] offset:1792 sc1
	global_load_dword v3, v129, s[50:51] offset:2048 sc1
	global_load_dword v4, v129, s[50:51] offset:2304 sc1
	global_load_dword v5, v129, s[50:51] offset:2560 sc1
	global_load_dword v6, v129, s[50:51] offset:2816 sc1
	global_load_dword v7, v129, s[50:51] offset:3072 sc1
	global_load_dword v8, v129, s[50:51] offset:3328 sc1
	global_load_dword v9, v129, s[50:51] offset:3584 sc1
	global_load_dword v10, v129, s[50:51] offset:3840 sc1
	global_load_dword v11, v129, s[38:39] sc1
	global_load_dword v13, v129, s[6:7] sc1
	v_readlane_b32 s6, v255, 5
	v_readlane_b32 s7, v255, 6
	s_mov_b64 s[12:13], -1
	s_waitcnt vmcnt(12)
	v_add_u32_e32 v16, v0, v12
	s_nop 1
	global_load_dword v14, v129, s[6:7] sc1
	v_readlane_b32 s6, v255, 7
	v_readlane_b32 s7, v255, 8
	s_waitcnt vmcnt(12)
	v_add_u32_e32 v16, v16, v1
	s_waitcnt vmcnt(11)
	v_add_u32_e32 v16, v16, v2
	s_waitcnt vmcnt(10)
	v_add_u32_e32 v16, v16, v3
	s_waitcnt vmcnt(9)
	v_add_u32_e32 v16, v16, v4
	s_waitcnt vmcnt(8)
	v_add_u32_e32 v16, v16, v5
	global_load_dword v15, v129, s[6:7] sc1
	s_waitcnt vmcnt(8)
	v_add_u32_e32 v16, v16, v6
	s_waitcnt vmcnt(7)
	v_add_u32_e32 v16, v16, v7
	s_waitcnt vmcnt(6)
	v_add_u32_e32 v16, v16, v8
	s_waitcnt vmcnt(5)
	v_add_u32_e32 v16, v16, v9
	s_waitcnt vmcnt(4)
	v_add_u32_e32 v16, v16, v10
	s_waitcnt vmcnt(3)
	v_add_u32_e32 v16, v16, v11
	s_waitcnt vmcnt(2)
	v_add_u32_e32 v16, v16, v13
	s_mov_b64 s[6:7], -1
	s_waitcnt vmcnt(1)
	v_add_u32_e32 v16, v16, v14
	s_waitcnt vmcnt(0)
	v_add_u32_e32 v16, v16, v15
	v_cmp_eq_u32_e32 vcc, s48, v16
	s_cbranch_vccnz .LBB0_1218
	s_and_b32 s6, s16, 0xff
	s_cmp_eq_u32 s6, 0
	s_mov_b64 s[6:7], -1
	s_mov_b64 s[14:15], -1
	s_nop 0
	s_cbranch_scc0 .LBB0_1223
	v_readlane_b32 s6, v255, 3
	v_readlane_b32 s7, v255, 4
	s_nop 4
	global_load_dword v16, v129, s[6:7] sc1
	s_waitcnt vmcnt(0)
	v_cmp_eq_u32_e32 vcc, 0, v16
	s_cbranch_vccnz .LBB0_1225
	s_mov_b64 s[14:15], 0
	s_mov_b64 s[6:7], -1

; __device__ __forceinline__ unsigned xb_ld(unsigned* p)              { return __hip_atomic_load(p, __ATOMIC_RELAXED, __HIP_MEMORY_SCOPE_AGENT); }
; __device__ __forceinline__ unsigned xb_add(unsigned* p, unsigned v) { return __hip_atomic_fetch_add(p, v, __ATOMIC_RELAXED, __HIP_MEMORY_SCOPE_AGENT); }
; #define XB_SPIN(cond, bar) do { unsigned _sp = 0; while (cond) { __builtin_amdgcn_s_sleep(1); \
;     if ((++_sp & 255u) == 0u) { if (xb_ld(&(bar)[XB_TMO])) break; if (_sp > XB_SPIN_CAP) { atomicAdd(&(bar)[XB_TMO], 1u); break; } } } } while (0)
; __device__ __forceinline__ void xcd_barrier(const XcdBarrier& b) {
;     ...
;             else XB_SPIN(xb_ld(&bar[XB_TOPGEN]) == tg, bar);
;             __builtin_amdgcn_fence(__ATOMIC_ACQUIRE, "agent");
;             xb_add(&bar[XB_XGEN(b.x)], 1u);
;             asm volatile("s_waitcnt vmcnt(0)" ::: "memory");
;         } else {
;             XB_SPIN(xb_ld(&bar[XB_XGEN(b.x)]) == gen, bar);
.LBB0_1233:
	s_and_b32 s20, s24, 0xff
	s_mov_b64 s[18:19], -1
	s_cmp_lg_u32 s20, 0
	s_mov_b64 s[22:23], -1
	s_nop 0
	s_cbranch_scc1 .LBB0_1236
	v_readlane_b32 s20, v255, 3
	v_readlane_b32 s21, v255, 4
	s_nop 4
	global_load_dword v1, v129, s[20:21] sc1
	s_waitcnt vmcnt(0)
	v_cmp_eq_u32_e32 vcc, 0, v1
	s_cbranch_vccnz .LBB0_1238
	s_mov_b64 s[22:23], 0
	s_mov_b64 s[20:21], -1

; __device__ __forceinline__ unsigned xb_ld(unsigned* p)              { return __hip_atomic_load(p, __ATOMIC_RELAXED, __HIP_MEMORY_SCOPE_AGENT); }
; __device__ __forceinline__ unsigned xb_add(unsigned* p, unsigned v) { return __hip_atomic_fetch_add(p, v, __ATOMIC_RELAXED, __HIP_MEMORY_SCOPE_AGENT); }
; #define XB_SPIN(cond, bar) do { unsigned _sp = 0; while (cond) { __builtin_amdgcn_s_sleep(1); \
;     if ((++_sp & 255u) == 0u) { if (xb_ld(&(bar)[XB_TMO])) break; if (_sp > XB_SPIN_CAP) { atomicAdd(&(bar)[XB_TMO], 1u); break; } } } } while (0)
; __device__ __forceinline__ void xcd_barrier(const XcdBarrier& b) {
;     ...
;             else XB_SPIN(xb_ld(&bar[XB_TOPGEN]) == tg, bar);
;             __builtin_amdgcn_fence(__ATOMIC_ACQUIRE, "agent");
;             xb_add(&bar[XB_XGEN(b.x)], 1u);
;             asm volatile("s_waitcnt vmcnt(0)" ::: "memory");
;         } else {
;             XB_SPIN(xb_ld(&bar[XB_XGEN(b.x)]) == gen, bar);
.LBB0_1247:
	s_and_b32 s20, s24, 0xff
	s_mov_b64 s[18:19], -1
	s_cmp_lg_u32 s20, 0
	s_mov_b64 s[22:23], -1
	s_nop 0
	s_cbranch_scc1 .LBB0_1250
	v_readlane_b32 s20, v255, 3
	v_readlane_b32 s21, v255, 4
	s_nop 4
	global_load_dword v0, v129, s[20:21] sc1
	s_waitcnt vmcnt(0)
	v_cmp_eq_u32_e32 vcc, 0, v0
	s_cbranch_vccnz .LBB0_1252
	s_mov_b64 s[22:23], 0
	s_mov_b64 s[20:21], -1
